# accumulator zero-init at each GEMM unit start: 127 v_mov_b32 replaced by 64 v_mov_b64 (16 GEMM instances)
# baseline (speedup 1.0000x reference)
;     __device__ __forceinline__ bool next(int i, Unit& u) const { const long L = (long)i * G + c; if (L >= map.total()) return false; map((int)L, u); return true; }
; template <class Epi, class Sched, bool SWAPD = false>
; __device__ __forceinline__ void gemm_phase(LAS unsigned char* lds, const Gemm g, const Sched& S, const Epi& E) {
;     ...
;         const bool has_next = S.next(ui + 1, nxt);
;         const char* nA = has_next ? (const char*)g.A + nxt.aoff : cA; const char* nB = has_next ? (const char*)g.Bt + nxt.boff : cB;
;         const int nt = cur.nt ? cur.nt : ntK;
;         for (int t = 0; t < nt; t += 2) {
;             const bool last = (t == nt - 2);
;             const char* a1 = cA + (size_t)(t + 1) * kstepA;
;             const char* a2 = last ? nA : cA + (size_t)(t + 2) * kstepA; const char* b2 = last ? nB : cB + (size_t)(t + 2) * kstep;
;             const char* a3 = a2 + kstepA; const char* b3 = b2 + kstep;
;     ...
; #pragma unroll
;         for (int a = 0; a < 2; ++a)
; #pragma unroll
;             for (int b = 0; b < 2; ++b)
; #pragma unroll
;                 for (int m = 0; m < 4; ++m)
; #pragma unroll
;                     for (int n = 0; n < 2; ++n) acc[a][b][m][n] = (f32x4){0.f, 0.f, 0.f, 0.f};
.LBB0_255:
	s_add_u32 s28, s18, s24
	s_addc_u32 s29, s19, s25
	s_and_b64 s[38:39], s[4:5], exec
	s_cselect_b32 s13, s29, s45
	s_cselect_b32 s23, s28, s44
	s_add_u32 s38, s95, s26
	s_addc_u32 s39, s30, s27
	s_and_b64 s[50:51], s[4:5], exec
	s_cselect_b32 s64, s39, s47
	s_cselect_b32 s65, s38, s46
	s_add_u32 s44, s44, 0x40080
	s_addc_u32 s45, s45, 0
	s_add_u32 s66, s46, 0x100
	v_mov_b32_e32 v0, 0
	s_addc_u32 s67, s47, 0
	s_mov_b32 s68, -2
	v_mov_b64_e32 v[0:1], 0
	v_mov_b64_e32 v[2:3], 0
	v_mov_b64_e32 v[4:5], 0
	v_mov_b64_e32 v[6:7], 0
	v_mov_b64_e32 v[8:9], 0
	v_mov_b64_e32 v[10:11], 0
	v_mov_b64_e32 v[12:13], 0
	v_mov_b64_e32 v[14:15], 0
	v_mov_b64_e32 v[16:17], 0
	v_mov_b64_e32 v[18:19], 0
	v_mov_b64_e32 v[20:21], 0
	v_mov_b64_e32 v[22:23], 0
	v_mov_b64_e32 v[24:25], 0
	v_mov_b64_e32 v[26:27], 0
	v_mov_b64_e32 v[28:29], 0
	v_mov_b64_e32 v[30:31], 0
	v_mov_b64_e32 v[32:33], 0
	v_mov_b64_e32 v[34:35], 0
	v_mov_b64_e32 v[36:37], 0
	v_mov_b64_e32 v[38:39], 0
	v_mov_b64_e32 v[40:41], 0
	v_mov_b64_e32 v[42:43], 0
	v_mov_b64_e32 v[44:45], 0
	v_mov_b64_e32 v[46:47], 0
	v_mov_b64_e32 v[48:49], 0
	v_mov_b64_e32 v[50:51], 0
	v_mov_b64_e32 v[52:53], 0
	v_mov_b64_e32 v[54:55], 0
	v_mov_b64_e32 v[56:57], 0
	v_mov_b64_e32 v[58:59], 0
	v_mov_b64_e32 v[60:61], 0
	v_mov_b64_e32 v[62:63], 0
	v_mov_b64_e32 v[64:65], 0
	v_mov_b64_e32 v[66:67], 0
	v_mov_b64_e32 v[68:69], 0
	v_mov_b64_e32 v[70:71], 0
	v_mov_b64_e32 v[72:73], 0
	v_mov_b64_e32 v[74:75], 0
	v_mov_b64_e32 v[76:77], 0
	v_mov_b64_e32 v[78:79], 0
	v_mov_b64_e32 v[80:81], 0
	v_mov_b64_e32 v[82:83], 0
	v_mov_b64_e32 v[84:85], 0
	v_mov_b64_e32 v[86:87], 0
	v_mov_b64_e32 v[88:89], 0
	v_mov_b64_e32 v[90:91], 0
	v_mov_b64_e32 v[92:93], 0
	v_mov_b64_e32 v[94:95], 0
	v_mov_b64_e32 v[96:97], 0
	v_mov_b64_e32 v[98:99], 0
	v_mov_b64_e32 v[100:101], 0
	v_mov_b64_e32 v[102:103], 0
	v_mov_b64_e32 v[104:105], 0
	v_mov_b64_e32 v[106:107], 0
	v_mov_b64_e32 v[108:109], 0
	v_mov_b64_e32 v[110:111], 0
	v_mov_b64_e32 v[112:113], 0
	v_mov_b64_e32 v[114:115], 0
	v_mov_b64_e32 v[116:117], 0
	v_mov_b64_e32 v[118:119], 0
	v_mov_b64_e32 v[120:121], 0
	v_mov_b64_e32 v[122:123], 0
	v_mov_b64_e32 v[124:125], 0
	v_mov_b64_e32 v[126:127], 0

;     __device__ __forceinline__ bool next(int i, Unit& u) const { const long L = (long)i * G + c; if (L >= map.total()) return false; map((int)L, u); return true; }
; template <class Epi, class Sched, bool SWAPD = false>
; __device__ __forceinline__ void gemm_phase(LAS unsigned char* lds, const Gemm g, const Sched& S, const Epi& E) {
;     ...
;         const bool has_next = S.next(ui + 1, nxt);
;         const char* nA = has_next ? (const char*)g.A + nxt.aoff : cA; const char* nB = has_next ? (const char*)g.Bt + nxt.boff : cB;
;         const int nt = cur.nt ? cur.nt : ntK;
;         for (int t = 0; t < nt; t += 2) {
;             const bool last = (t == nt - 2);
;             const char* a1 = cA + (size_t)(t + 1) * kstepA;
;             const char* a2 = last ? nA : cA + (size_t)(t + 2) * kstepA; const char* b2 = last ? nB : cB + (size_t)(t + 2) * kstep;
;             const char* a3 = a2 + kstepA; const char* b3 = b2 + kstep;
;     ...
; #pragma unroll
;         for (int a = 0; a < 2; ++a)
; #pragma unroll
;             for (int b = 0; b < 2; ++b)
; #pragma unroll
;                 for (int m = 0; m < 4; ++m)
; #pragma unroll
;                     for (int n = 0; n < 2; ++n) acc[a][b][m][n] = (f32x4){0.f, 0.f, 0.f, 0.f};
.LBB0_351:
	s_add_u32 s24, s14, s12
	s_addc_u32 s25, s15, s13
	s_add_u32 s26, s80, s22
	s_addc_u32 s27, s81, s23
	s_cmp_lg_u32 s29, 0
	s_cselect_b32 s0, s29, 44
	s_cmp_lt_i32 s0, 1
	s_cbranch_scc1 .LBB0_358
	s_and_b64 s[34:35], s[4:5], exec
	s_cselect_b32 s29, s25, s39
	s_cselect_b32 s33, s24, s38
	s_cselect_b32 s34, s27, s43
	s_cselect_b32 s35, s26, s42
	s_add_i32 s74, s0, -2
	s_add_u32 s75, s42, 0x100
	v_mov_b32_e32 v0, 0
	s_addc_u32 s76, s43, 0
	s_mov_b32 s44, 0
	v_mov_b64_e32 v[0:1], 0
	v_mov_b64_e32 v[2:3], 0
	v_mov_b64_e32 v[4:5], 0
	v_mov_b64_e32 v[6:7], 0
	v_mov_b64_e32 v[8:9], 0
	v_mov_b64_e32 v[10:11], 0
	v_mov_b64_e32 v[12:13], 0
	v_mov_b64_e32 v[14:15], 0
	v_mov_b64_e32 v[16:17], 0
	v_mov_b64_e32 v[18:19], 0
	v_mov_b64_e32 v[20:21], 0
	v_mov_b64_e32 v[22:23], 0
	v_mov_b64_e32 v[24:25], 0
	v_mov_b64_e32 v[26:27], 0
	v_mov_b64_e32 v[28:29], 0
	v_mov_b64_e32 v[30:31], 0
	v_mov_b64_e32 v[32:33], 0
	v_mov_b64_e32 v[34:35], 0
	v_mov_b64_e32 v[36:37], 0
	v_mov_b64_e32 v[38:39], 0
	v_mov_b64_e32 v[40:41], 0
	v_mov_b64_e32 v[42:43], 0
	v_mov_b64_e32 v[44:45], 0
	v_mov_b64_e32 v[46:47], 0
	v_mov_b64_e32 v[48:49], 0
	v_mov_b64_e32 v[50:51], 0
	v_mov_b64_e32 v[52:53], 0
	v_mov_b64_e32 v[54:55], 0
	v_mov_b64_e32 v[56:57], 0
	v_mov_b64_e32 v[58:59], 0
	v_mov_b64_e32 v[60:61], 0
	v_mov_b64_e32 v[62:63], 0
	v_mov_b64_e32 v[64:65], 0
	v_mov_b64_e32 v[66:67], 0
	v_mov_b64_e32 v[68:69], 0
	v_mov_b64_e32 v[70:71], 0
	v_mov_b64_e32 v[72:73], 0
	v_mov_b64_e32 v[74:75], 0
	v_mov_b64_e32 v[76:77], 0
	v_mov_b64_e32 v[78:79], 0
	v_mov_b64_e32 v[80:81], 0
	v_mov_b64_e32 v[82:83], 0
	v_mov_b64_e32 v[84:85], 0
	v_mov_b64_e32 v[86:87], 0
	v_mov_b64_e32 v[88:89], 0
	v_mov_b64_e32 v[90:91], 0
	v_mov_b64_e32 v[92:93], 0
	v_mov_b64_e32 v[94:95], 0
	v_mov_b64_e32 v[96:97], 0
	v_mov_b64_e32 v[98:99], 0
	v_mov_b64_e32 v[100:101], 0
	v_mov_b64_e32 v[102:103], 0
	v_mov_b64_e32 v[104:105], 0
	v_mov_b64_e32 v[106:107], 0
	v_mov_b64_e32 v[108:109], 0
	v_mov_b64_e32 v[110:111], 0
	v_mov_b64_e32 v[112:113], 0
	v_mov_b64_e32 v[114:115], 0
	v_mov_b64_e32 v[116:117], 0
	v_mov_b64_e32 v[118:119], 0
	v_mov_b64_e32 v[120:121], 0
	v_mov_b64_e32 v[122:123], 0
	v_mov_b64_e32 v[124:125], 0
	v_mov_b64_e32 v[126:127], 0

;     __device__ __forceinline__ bool next(int i, Unit& u) const { const long L = (long)i * G + c; if (L >= map.total()) return false; map((int)L, u); return true; }
; template <class Epi, class Sched, bool SWAPD = false>
; __device__ __forceinline__ void gemm_phase(LAS unsigned char* lds, const Gemm g, const Sched& S, const Epi& E) {
;     ...
;         const bool has_next = S.next(ui + 1, nxt);
;         const char* nA = has_next ? (const char*)g.A + nxt.aoff : cA; const char* nB = has_next ? (const char*)g.Bt + nxt.boff : cB;
;         const int nt = cur.nt ? cur.nt : ntK;
;         for (int t = 0; t < nt; t += 2) {
;             const bool last = (t == nt - 2);
;             const char* a1 = cA + (size_t)(t + 1) * kstepA;
;             const char* a2 = last ? nA : cA + (size_t)(t + 2) * kstepA; const char* b2 = last ? nB : cB + (size_t)(t + 2) * kstep;
;             const char* a3 = a2 + kstepA; const char* b3 = b2 + kstep;
;     ...
; #pragma unroll
;         for (int a = 0; a < 2; ++a)
; #pragma unroll
;             for (int b = 0; b < 2; ++b)
; #pragma unroll
;                 for (int m = 0; m < 4; ++m)
; #pragma unroll
;                     for (int n = 0; n < 2; ++n) acc[a][b][m][n] = (f32x4){0.f, 0.f, 0.f, 0.f};
.LBB0_485:
	s_add_u32 s36, s18, s26
	s_addc_u32 s37, s19, s27
	s_and_b64 s[38:39], s[4:5], exec
	s_cselect_b32 s7, s37, s41
	s_cselect_b32 s13, s36, s40
	s_add_u32 s38, s96, s28
	s_addc_u32 s39, s97, s29
	s_and_b64 s[44:45], s[4:5], exec
	s_cselect_b32 s25, s39, s43
	s_cselect_b32 s57, s38, s42
	s_add_u32 s40, s40, 0x40080
	s_addc_u32 s41, s41, 0
	s_add_u32 s64, s42, 0x100
	v_mov_b32_e32 v0, 0
	s_addc_u32 s65, s43, 0
	s_mov_b32 s66, -2
	v_mov_b64_e32 v[0:1], 0
	v_mov_b64_e32 v[2:3], 0
	v_mov_b64_e32 v[4:5], 0
	v_mov_b64_e32 v[6:7], 0
	v_mov_b64_e32 v[8:9], 0
	v_mov_b64_e32 v[10:11], 0
	v_mov_b64_e32 v[12:13], 0
	v_mov_b64_e32 v[14:15], 0
	v_mov_b64_e32 v[16:17], 0
	v_mov_b64_e32 v[18:19], 0
	v_mov_b64_e32 v[20:21], 0
	v_mov_b64_e32 v[22:23], 0
	v_mov_b64_e32 v[24:25], 0
	v_mov_b64_e32 v[26:27], 0
	v_mov_b64_e32 v[28:29], 0
	v_mov_b64_e32 v[30:31], 0
	v_mov_b64_e32 v[32:33], 0
	v_mov_b64_e32 v[34:35], 0
	v_mov_b64_e32 v[36:37], 0
	v_mov_b64_e32 v[38:39], 0
	v_mov_b64_e32 v[40:41], 0
	v_mov_b64_e32 v[42:43], 0
	v_mov_b64_e32 v[44:45], 0
	v_mov_b64_e32 v[46:47], 0
	v_mov_b64_e32 v[48:49], 0
	v_mov_b64_e32 v[50:51], 0
	v_mov_b64_e32 v[52:53], 0
	v_mov_b64_e32 v[54:55], 0
	v_mov_b64_e32 v[56:57], 0
	v_mov_b64_e32 v[58:59], 0
	v_mov_b64_e32 v[60:61], 0
	v_mov_b64_e32 v[62:63], 0
	v_mov_b64_e32 v[64:65], 0
	v_mov_b64_e32 v[66:67], 0
	v_mov_b64_e32 v[68:69], 0
	v_mov_b64_e32 v[70:71], 0
	v_mov_b64_e32 v[72:73], 0
	v_mov_b64_e32 v[74:75], 0
	v_mov_b64_e32 v[76:77], 0
	v_mov_b64_e32 v[78:79], 0
	v_mov_b64_e32 v[80:81], 0
	v_mov_b64_e32 v[82:83], 0
	v_mov_b64_e32 v[84:85], 0
	v_mov_b64_e32 v[86:87], 0
	v_mov_b64_e32 v[88:89], 0
	v_mov_b64_e32 v[90:91], 0
	v_mov_b64_e32 v[92:93], 0
	v_mov_b64_e32 v[94:95], 0
	v_mov_b64_e32 v[96:97], 0
	v_mov_b64_e32 v[98:99], 0
	v_mov_b64_e32 v[100:101], 0
	v_mov_b64_e32 v[102:103], 0
	v_mov_b64_e32 v[104:105], 0
	v_mov_b64_e32 v[106:107], 0
	v_mov_b64_e32 v[108:109], 0
	v_mov_b64_e32 v[110:111], 0
	v_mov_b64_e32 v[112:113], 0
	v_mov_b64_e32 v[114:115], 0
	v_mov_b64_e32 v[116:117], 0
	v_mov_b64_e32 v[118:119], 0
	v_mov_b64_e32 v[120:121], 0
	v_mov_b64_e32 v[122:123], 0
	v_mov_b64_e32 v[124:125], 0
	v_mov_b64_e32 v[126:127], 0

;     __device__ __forceinline__ bool next(int i, Unit& u) const { const long L = (long)i * G + c; if (L >= map.total()) return false; map((int)L, u); return true; }
; template <class Epi, class Sched, bool SWAPD = false>
; __device__ __forceinline__ void gemm_phase(LAS unsigned char* lds, const Gemm g, const Sched& S, const Epi& E) {
;     ...
;         const bool has_next = S.next(ui + 1, nxt);
;         const char* nA = has_next ? (const char*)g.A + nxt.aoff : cA; const char* nB = has_next ? (const char*)g.Bt + nxt.boff : cB;
;         const int nt = cur.nt ? cur.nt : ntK;
;         for (int t = 0; t < nt; t += 2) {
;             const bool last = (t == nt - 2);
;             const char* a1 = cA + (size_t)(t + 1) * kstepA;
;             const char* a2 = last ? nA : cA + (size_t)(t + 2) * kstepA; const char* b2 = last ? nB : cB + (size_t)(t + 2) * kstep;
;             const char* a3 = a2 + kstepA; const char* b3 = b2 + kstep;
;     ...
; #pragma unroll
;         for (int a = 0; a < 2; ++a)
; #pragma unroll
;             for (int b = 0; b < 2; ++b)
; #pragma unroll
;                 for (int m = 0; m < 4; ++m)
; #pragma unroll
;                     for (int n = 0; n < 2; ++n) acc[a][b][m][n] = (f32x4){0.f, 0.f, 0.f, 0.f};
.LBB0_632:
	s_add_u32 s44, s22, s40
	s_addc_u32 s45, s23, s41
	s_and_b64 s[46:47], s[4:5], exec
	s_cselect_b32 s75, s45, s51
	s_cselect_b32 s76, s44, s50
	s_add_u32 s46, s30, s42
	s_addc_u32 s47, s31, s43
	s_and_b64 s[54:55], s[4:5], exec
	s_cselect_b32 s77, s47, s53
	s_cselect_b32 s78, s46, s52
	s_add_u32 s79, s52, 0x100
	v_mov_b32_e32 v0, 0
	s_addc_u32 s80, s53, 0
	s_mov_b32 s81, -2
	v_mov_b64_e32 v[0:1], 0
	v_mov_b64_e32 v[2:3], 0
	v_mov_b64_e32 v[4:5], 0
	v_mov_b64_e32 v[6:7], 0
	v_mov_b64_e32 v[8:9], 0
	v_mov_b64_e32 v[10:11], 0
	v_mov_b64_e32 v[12:13], 0
	v_mov_b64_e32 v[14:15], 0
	v_mov_b64_e32 v[16:17], 0
	v_mov_b64_e32 v[18:19], 0
	v_mov_b64_e32 v[20:21], 0
	v_mov_b64_e32 v[22:23], 0
	v_mov_b64_e32 v[24:25], 0
	v_mov_b64_e32 v[26:27], 0
	v_mov_b64_e32 v[28:29], 0
	v_mov_b64_e32 v[30:31], 0
	v_mov_b64_e32 v[32:33], 0
	v_mov_b64_e32 v[34:35], 0
	v_mov_b64_e32 v[36:37], 0
	v_mov_b64_e32 v[38:39], 0
	v_mov_b64_e32 v[40:41], 0
	v_mov_b64_e32 v[42:43], 0
	v_mov_b64_e32 v[44:45], 0
	v_mov_b64_e32 v[46:47], 0
	v_mov_b64_e32 v[48:49], 0
	v_mov_b64_e32 v[50:51], 0
	v_mov_b64_e32 v[52:53], 0
	v_mov_b64_e32 v[54:55], 0
	v_mov_b64_e32 v[56:57], 0
	v_mov_b64_e32 v[58:59], 0
	v_mov_b64_e32 v[60:61], 0
	v_mov_b64_e32 v[62:63], 0
	v_mov_b64_e32 v[64:65], 0
	v_mov_b64_e32 v[66:67], 0
	v_mov_b64_e32 v[68:69], 0
	v_mov_b64_e32 v[70:71], 0
	v_mov_b64_e32 v[72:73], 0
	v_mov_b64_e32 v[74:75], 0
	v_mov_b64_e32 v[76:77], 0
	v_mov_b64_e32 v[78:79], 0
	v_mov_b64_e32 v[80:81], 0
	v_mov_b64_e32 v[82:83], 0
	v_mov_b64_e32 v[84:85], 0
	v_mov_b64_e32 v[86:87], 0
	v_mov_b64_e32 v[88:89], 0
	v_mov_b64_e32 v[90:91], 0
	v_mov_b64_e32 v[92:93], 0
	v_mov_b64_e32 v[94:95], 0
	v_mov_b64_e32 v[96:97], 0
	v_mov_b64_e32 v[98:99], 0
	v_mov_b64_e32 v[100:101], 0
	v_mov_b64_e32 v[102:103], 0
	v_mov_b64_e32 v[104:105], 0
	v_mov_b64_e32 v[106:107], 0
	v_mov_b64_e32 v[108:109], 0
	v_mov_b64_e32 v[110:111], 0
	v_mov_b64_e32 v[112:113], 0
	v_mov_b64_e32 v[114:115], 0
	v_mov_b64_e32 v[116:117], 0
	v_mov_b64_e32 v[118:119], 0
	v_mov_b64_e32 v[120:121], 0
	v_mov_b64_e32 v[122:123], 0
	v_mov_b64_e32 v[124:125], 0
	v_mov_b64_e32 v[126:127], 0

;     __device__ __forceinline__ bool next(int i, Unit& u) const { const long L = (long)i * G + c; if (L >= map.total()) return false; map((int)L, u); return true; }
; template <class Epi, class Sched, bool SWAPD = false>
; __device__ __forceinline__ void gemm_phase(LAS unsigned char* lds, const Gemm g, const Sched& S, const Epi& E) {
;     ...
;         const bool has_next = S.next(ui + 1, nxt);
;         const char* nA = has_next ? (const char*)g.A + nxt.aoff : cA; const char* nB = has_next ? (const char*)g.Bt + nxt.boff : cB;
;         const int nt = cur.nt ? cur.nt : ntK;
;         for (int t = 0; t < nt; t += 2) {
;             const bool last = (t == nt - 2);
;             const char* a1 = cA + (size_t)(t + 1) * kstepA;
;             const char* a2 = last ? nA : cA + (size_t)(t + 2) * kstepA; const char* b2 = last ? nB : cB + (size_t)(t + 2) * kstep;
;             const char* a3 = a2 + kstepA; const char* b3 = b2 + kstep;
;     ...
; #pragma unroll
;         for (int a = 0; a < 2; ++a)
; #pragma unroll
;             for (int b = 0; b < 2; ++b)
; #pragma unroll
;                 for (int m = 0; m < 4; ++m)
; #pragma unroll
;                     for (int n = 0; n < 2; ++n) acc[a][b][m][n] = (f32x4){0.f, 0.f, 0.f, 0.f};
.LBB0_765:
	s_add_u32 s36, s22, s26
	s_addc_u32 s37, s23, s27
	s_and_b64 s[38:39], s[4:5], exec
	s_cselect_b32 s61, s37, s41
	s_cselect_b32 s62, s36, s40
	s_add_u32 s38, s30, s28
	s_addc_u32 s39, s31, s29
	s_and_b64 s[44:45], s[4:5], exec
	s_cselect_b32 s63, s39, s43
	s_cselect_b32 s64, s38, s42
	s_add_u32 s65, s42, 0x100
	v_mov_b32_e32 v0, 0
	s_addc_u32 s66, s43, 0
	s_mov_b32 s67, -2
	v_mov_b64_e32 v[0:1], 0
	v_mov_b64_e32 v[2:3], 0
	v_mov_b64_e32 v[4:5], 0
	v_mov_b64_e32 v[6:7], 0
	v_mov_b64_e32 v[8:9], 0
	v_mov_b64_e32 v[10:11], 0
	v_mov_b64_e32 v[12:13], 0
	v_mov_b64_e32 v[14:15], 0
	v_mov_b64_e32 v[16:17], 0
	v_mov_b64_e32 v[18:19], 0
	v_mov_b64_e32 v[20:21], 0
	v_mov_b64_e32 v[22:23], 0
	v_mov_b64_e32 v[24:25], 0
	v_mov_b64_e32 v[26:27], 0
	v_mov_b64_e32 v[28:29], 0
	v_mov_b64_e32 v[30:31], 0
	v_mov_b64_e32 v[32:33], 0
	v_mov_b64_e32 v[34:35], 0
	v_mov_b64_e32 v[36:37], 0
	v_mov_b64_e32 v[38:39], 0
	v_mov_b64_e32 v[40:41], 0
	v_mov_b64_e32 v[42:43], 0
	v_mov_b64_e32 v[44:45], 0
	v_mov_b64_e32 v[46:47], 0
	v_mov_b64_e32 v[48:49], 0
	v_mov_b64_e32 v[50:51], 0
	v_mov_b64_e32 v[52:53], 0
	v_mov_b64_e32 v[54:55], 0
	v_mov_b64_e32 v[56:57], 0
	v_mov_b64_e32 v[58:59], 0
	v_mov_b64_e32 v[60:61], 0
	v_mov_b64_e32 v[62:63], 0
	v_mov_b64_e32 v[64:65], 0
	v_mov_b64_e32 v[66:67], 0
	v_mov_b64_e32 v[68:69], 0
	v_mov_b64_e32 v[70:71], 0
	v_mov_b64_e32 v[72:73], 0
	v_mov_b64_e32 v[74:75], 0
	v_mov_b64_e32 v[76:77], 0
	v_mov_b64_e32 v[78:79], 0
	v_mov_b64_e32 v[80:81], 0
	v_mov_b64_e32 v[82:83], 0
	v_mov_b64_e32 v[84:85], 0
	v_mov_b64_e32 v[86:87], 0
	v_mov_b64_e32 v[88:89], 0
	v_mov_b64_e32 v[90:91], 0
	v_mov_b64_e32 v[92:93], 0
	v_mov_b64_e32 v[94:95], 0
	v_mov_b64_e32 v[96:97], 0
	v_mov_b64_e32 v[98:99], 0
	v_mov_b64_e32 v[100:101], 0
	v_mov_b64_e32 v[102:103], 0
	v_mov_b64_e32 v[104:105], 0
	v_mov_b64_e32 v[106:107], 0
	v_mov_b64_e32 v[108:109], 0
	v_mov_b64_e32 v[110:111], 0
	v_mov_b64_e32 v[112:113], 0
	v_mov_b64_e32 v[114:115], 0
	v_mov_b64_e32 v[116:117], 0
	v_mov_b64_e32 v[118:119], 0
	v_mov_b64_e32 v[120:121], 0
	v_mov_b64_e32 v[122:123], 0
	v_mov_b64_e32 v[124:125], 0
	v_mov_b64_e32 v[126:127], 0

;     __device__ __forceinline__ bool next(int i, Unit& u) const { const long L = (long)i * G + c; if (L >= map.total()) return false; map((int)L, u); return true; }
; template <class Epi, class Sched, bool SWAPD = false>
; __device__ __forceinline__ void gemm_phase(LAS unsigned char* lds, const Gemm g, const Sched& S, const Epi& E) {
;     ...
;         const bool has_next = S.next(ui + 1, nxt);
;         const char* nA = has_next ? (const char*)g.A + nxt.aoff : cA; const char* nB = has_next ? (const char*)g.Bt + nxt.boff : cB;
;         const int nt = cur.nt ? cur.nt : ntK;
;         for (int t = 0; t < nt; t += 2) {
;             const bool last = (t == nt - 2);
;             const char* a1 = cA + (size_t)(t + 1) * kstepA;
;             const char* a2 = last ? nA : cA + (size_t)(t + 2) * kstepA; const char* b2 = last ? nB : cB + (size_t)(t + 2) * kstep;
;             const char* a3 = a2 + kstepA; const char* b3 = b2 + kstep;
;     ...
; #pragma unroll
;         for (int a = 0; a < 2; ++a)
; #pragma unroll
;             for (int b = 0; b < 2; ++b)
; #pragma unroll
;                 for (int m = 0; m < 4; ++m)
; #pragma unroll
;                     for (int n = 0; n < 2; ++n) acc[a][b][m][n] = (f32x4){0.f, 0.f, 0.f, 0.f};
.LBB0_841:
	s_add_u32 s36, s0, s26
	s_addc_u32 s37, s1, s27
	s_and_b64 s[38:39], s[4:5], exec
	v_readlane_b32 s38, v254, 8
	s_cselect_b32 s23, s37, s43
	s_cselect_b32 s25, s36, s42
	v_readlane_b32 s39, v254, 9
	s_add_u32 s38, s38, s28
	s_addc_u32 s39, s39, s29
	s_and_b64 s[46:47], s[4:5], exec
	s_cselect_b32 s35, s39, s45
	s_cselect_b32 s59, s38, s44
	s_add_u32 s60, s44, 0x100
	v_mov_b32_e32 v0, 0
	s_addc_u32 s61, s45, 0
	s_mov_b32 s62, -2
	v_mov_b64_e32 v[0:1], 0
	v_mov_b64_e32 v[2:3], 0
	v_mov_b64_e32 v[4:5], 0
	v_mov_b64_e32 v[6:7], 0
	v_mov_b64_e32 v[8:9], 0
	v_mov_b64_e32 v[10:11], 0
	v_mov_b64_e32 v[12:13], 0
	v_mov_b64_e32 v[14:15], 0
	v_mov_b64_e32 v[16:17], 0
	v_mov_b64_e32 v[18:19], 0
	v_mov_b64_e32 v[20:21], 0
	v_mov_b64_e32 v[22:23], 0
	v_mov_b64_e32 v[24:25], 0
	v_mov_b64_e32 v[26:27], 0
	v_mov_b64_e32 v[28:29], 0
	v_mov_b64_e32 v[30:31], 0
	v_mov_b64_e32 v[32:33], 0
	v_mov_b64_e32 v[34:35], 0
	v_mov_b64_e32 v[36:37], 0
	v_mov_b64_e32 v[38:39], 0
	v_mov_b64_e32 v[40:41], 0
	v_mov_b64_e32 v[42:43], 0
	v_mov_b64_e32 v[44:45], 0
	v_mov_b64_e32 v[46:47], 0
	v_mov_b64_e32 v[48:49], 0
	v_mov_b64_e32 v[50:51], 0
	v_mov_b64_e32 v[52:53], 0
	v_mov_b64_e32 v[54:55], 0
	v_mov_b64_e32 v[56:57], 0
	v_mov_b64_e32 v[58:59], 0
	v_mov_b64_e32 v[60:61], 0
	v_mov_b64_e32 v[62:63], 0
	v_mov_b64_e32 v[64:65], 0
	v_mov_b64_e32 v[66:67], 0
	v_mov_b64_e32 v[68:69], 0
	v_mov_b64_e32 v[70:71], 0
	v_mov_b64_e32 v[72:73], 0
	v_mov_b64_e32 v[74:75], 0
	v_mov_b64_e32 v[76:77], 0
	v_mov_b64_e32 v[78:79], 0
	v_mov_b64_e32 v[80:81], 0
	v_mov_b64_e32 v[82:83], 0
	v_mov_b64_e32 v[84:85], 0
	v_mov_b64_e32 v[86:87], 0
	v_mov_b64_e32 v[88:89], 0
	v_mov_b64_e32 v[90:91], 0
	v_mov_b64_e32 v[92:93], 0
	v_mov_b64_e32 v[94:95], 0
	v_mov_b64_e32 v[96:97], 0
	v_mov_b64_e32 v[98:99], 0
	v_mov_b64_e32 v[100:101], 0
	v_mov_b64_e32 v[102:103], 0
	v_mov_b64_e32 v[104:105], 0
	v_mov_b64_e32 v[106:107], 0
	v_mov_b64_e32 v[108:109], 0
	v_mov_b64_e32 v[110:111], 0
	v_mov_b64_e32 v[112:113], 0
	v_mov_b64_e32 v[114:115], 0
	v_mov_b64_e32 v[116:117], 0
	v_mov_b64_e32 v[118:119], 0
	v_mov_b64_e32 v[120:121], 0
	v_mov_b64_e32 v[122:123], 0
	v_mov_b64_e32 v[124:125], 0
	v_mov_b64_e32 v[126:127], 0

;     __device__ __forceinline__ bool next(int i, Unit& u) const { const long L = (long)i * G + c; if (L >= map.total()) return false; map((int)L, u); return true; }
; template <class Epi, class Sched, bool SWAPD = false>
; __device__ __forceinline__ void gemm_phase(LAS unsigned char* lds, const Gemm g, const Sched& S, const Epi& E) {
;     ...
;         const bool has_next = S.next(ui + 1, nxt);
;         const char* nA = has_next ? (const char*)g.A + nxt.aoff : cA; const char* nB = has_next ? (const char*)g.Bt + nxt.boff : cB;
;         const int nt = cur.nt ? cur.nt : ntK;
;         for (int t = 0; t < nt; t += 2) {
;             const bool last = (t == nt - 2);
;             const char* a1 = cA + (size_t)(t + 1) * kstepA;
;             const char* a2 = last ? nA : cA + (size_t)(t + 2) * kstepA; const char* b2 = last ? nB : cB + (size_t)(t + 2) * kstep;
;             const char* a3 = a2 + kstepA; const char* b3 = b2 + kstep;
;     ...
; #pragma unroll
;         for (int a = 0; a < 2; ++a)
; #pragma unroll
;             for (int b = 0; b < 2; ++b)
; #pragma unroll
;                 for (int m = 0; m < 4; ++m)
; #pragma unroll
;                     for (int n = 0; n < 2; ++n) acc[a][b][m][n] = (f32x4){0.f, 0.f, 0.f, 0.f};
.LBB0_917:
	s_add_u32 s36, s6, s26
	s_addc_u32 s37, s7, s27
	s_and_b64 s[38:39], s[4:5], exec
	v_readlane_b32 s38, v254, 6
	s_cselect_b32 s23, s37, s43
	s_cselect_b32 s25, s36, s42
	v_readlane_b32 s39, v254, 7
	s_add_u32 s38, s38, s28
	s_addc_u32 s39, s39, s29
	s_and_b64 s[46:47], s[4:5], exec
	s_cselect_b32 s35, s39, s45
	s_cselect_b32 s41, s38, s44
	s_add_u32 s42, s42, 0x40080
	s_addc_u32 s43, s43, 0
	s_add_u32 s58, s44, 0x100
	v_mov_b32_e32 v0, 0
	s_addc_u32 s59, s45, 0
	s_mov_b32 s60, -2
	v_mov_b64_e32 v[0:1], 0
	v_mov_b64_e32 v[2:3], 0
	v_mov_b64_e32 v[4:5], 0
	v_mov_b64_e32 v[6:7], 0
	v_mov_b64_e32 v[8:9], 0
	v_mov_b64_e32 v[10:11], 0
	v_mov_b64_e32 v[12:13], 0
	v_mov_b64_e32 v[14:15], 0
	v_mov_b64_e32 v[16:17], 0
	v_mov_b64_e32 v[18:19], 0
	v_mov_b64_e32 v[20:21], 0
	v_mov_b64_e32 v[22:23], 0
	v_mov_b64_e32 v[24:25], 0
	v_mov_b64_e32 v[26:27], 0
	v_mov_b64_e32 v[28:29], 0
	v_mov_b64_e32 v[30:31], 0
	v_mov_b64_e32 v[32:33], 0
	v_mov_b64_e32 v[34:35], 0
	v_mov_b64_e32 v[36:37], 0
	v_mov_b64_e32 v[38:39], 0
	v_mov_b64_e32 v[40:41], 0
	v_mov_b64_e32 v[42:43], 0
	v_mov_b64_e32 v[44:45], 0
	v_mov_b64_e32 v[46:47], 0
	v_mov_b64_e32 v[48:49], 0
	v_mov_b64_e32 v[50:51], 0
	v_mov_b64_e32 v[52:53], 0
	v_mov_b64_e32 v[54:55], 0
	v_mov_b64_e32 v[56:57], 0
	v_mov_b64_e32 v[58:59], 0
	v_mov_b64_e32 v[60:61], 0
	v_mov_b64_e32 v[62:63], 0
	v_mov_b64_e32 v[64:65], 0
	v_mov_b64_e32 v[66:67], 0
	v_mov_b64_e32 v[68:69], 0
	v_mov_b64_e32 v[70:71], 0
	v_mov_b64_e32 v[72:73], 0
	v_mov_b64_e32 v[74:75], 0
	v_mov_b64_e32 v[76:77], 0
	v_mov_b64_e32 v[78:79], 0
	v_mov_b64_e32 v[80:81], 0
	v_mov_b64_e32 v[82:83], 0
	v_mov_b64_e32 v[84:85], 0
	v_mov_b64_e32 v[86:87], 0
	v_mov_b64_e32 v[88:89], 0
	v_mov_b64_e32 v[90:91], 0
	v_mov_b64_e32 v[92:93], 0
	v_mov_b64_e32 v[94:95], 0
	v_mov_b64_e32 v[96:97], 0
	v_mov_b64_e32 v[98:99], 0
	v_mov_b64_e32 v[100:101], 0
	v_mov_b64_e32 v[102:103], 0
	v_mov_b64_e32 v[104:105], 0
	v_mov_b64_e32 v[106:107], 0
	v_mov_b64_e32 v[108:109], 0
	v_mov_b64_e32 v[110:111], 0
	v_mov_b64_e32 v[112:113], 0
	v_mov_b64_e32 v[114:115], 0
	v_mov_b64_e32 v[116:117], 0
	v_mov_b64_e32 v[118:119], 0
	v_mov_b64_e32 v[120:121], 0
	v_mov_b64_e32 v[122:123], 0
	v_mov_b64_e32 v[124:125], 0
	v_mov_b64_e32 v[126:127], 0

;     __device__ __forceinline__ bool next(int i, Unit& u) const { const long L = (long)i * G + c; if (L >= map.total()) return false; map((int)L, u); return true; }
; template <class Epi, class Sched, bool SWAPD = false>
; __device__ __forceinline__ void gemm_phase(LAS unsigned char* lds, const Gemm g, const Sched& S, const Epi& E) {
;     ...
;         const bool has_next = S.next(ui + 1, nxt);
;         const char* nA = has_next ? (const char*)g.A + nxt.aoff : cA; const char* nB = has_next ? (const char*)g.Bt + nxt.boff : cB;
;         const int nt = cur.nt ? cur.nt : ntK;
;         for (int t = 0; t < nt; t += 2) {
;             const bool last = (t == nt - 2);
;             const char* a1 = cA + (size_t)(t + 1) * kstepA;
;             const char* a2 = last ? nA : cA + (size_t)(t + 2) * kstepA; const char* b2 = last ? nB : cB + (size_t)(t + 2) * kstep;
;             const char* a3 = a2 + kstepA; const char* b3 = b2 + kstep;
;     ...
; #pragma unroll
;         for (int a = 0; a < 2; ++a)
; #pragma unroll
;             for (int b = 0; b < 2; ++b)
; #pragma unroll
;                 for (int m = 0; m < 4; ++m)
; #pragma unroll
;                     for (int n = 0; n < 2; ++n) acc[a][b][m][n] = (f32x4){0.f, 0.f, 0.f, 0.f};
.LBB0_1043:
	s_add_u32 s36, s18, s28
	s_addc_u32 s37, s19, s29
	s_and_b64 s[38:39], s[4:5], exec
	s_cselect_b32 s25, s37, s43
	s_cselect_b32 s27, s36, s42
	s_add_u32 s38, s21, s34
	s_addc_u32 s39, s23, s35
	s_and_b64 s[46:47], s[4:5], exec
	s_cselect_b32 s59, s39, s45
	s_cselect_b32 s60, s38, s44
	s_add_u32 s42, s42, 0x40080
	s_addc_u32 s43, s43, 0
	s_add_u32 s61, s44, 0x100
	v_mov_b32_e32 v0, 0
	s_addc_u32 s62, s45, 0
	s_mov_b32 s63, -2
	v_mov_b64_e32 v[0:1], 0
	v_mov_b64_e32 v[2:3], 0
	v_mov_b64_e32 v[4:5], 0
	v_mov_b64_e32 v[6:7], 0
	v_mov_b64_e32 v[8:9], 0
	v_mov_b64_e32 v[10:11], 0
	v_mov_b64_e32 v[12:13], 0
	v_mov_b64_e32 v[14:15], 0
	v_mov_b64_e32 v[16:17], 0
	v_mov_b64_e32 v[18:19], 0
	v_mov_b64_e32 v[20:21], 0
	v_mov_b64_e32 v[22:23], 0
	v_mov_b64_e32 v[24:25], 0
	v_mov_b64_e32 v[26:27], 0
	v_mov_b64_e32 v[28:29], 0
	v_mov_b64_e32 v[30:31], 0
	v_mov_b64_e32 v[32:33], 0
	v_mov_b64_e32 v[34:35], 0
	v_mov_b64_e32 v[36:37], 0
	v_mov_b64_e32 v[38:39], 0
	v_mov_b64_e32 v[40:41], 0
	v_mov_b64_e32 v[42:43], 0
	v_mov_b64_e32 v[44:45], 0
	v_mov_b64_e32 v[46:47], 0
	v_mov_b64_e32 v[48:49], 0
	v_mov_b64_e32 v[50:51], 0
	v_mov_b64_e32 v[52:53], 0
	v_mov_b64_e32 v[54:55], 0
	v_mov_b64_e32 v[56:57], 0
	v_mov_b64_e32 v[58:59], 0
	v_mov_b64_e32 v[60:61], 0
	v_mov_b64_e32 v[62:63], 0
	v_mov_b64_e32 v[64:65], 0
	v_mov_b64_e32 v[66:67], 0
	v_mov_b64_e32 v[68:69], 0
	v_mov_b64_e32 v[70:71], 0
	v_mov_b64_e32 v[72:73], 0
	v_mov_b64_e32 v[74:75], 0
	v_mov_b64_e32 v[76:77], 0
	v_mov_b64_e32 v[78:79], 0
	v_mov_b64_e32 v[80:81], 0
	v_mov_b64_e32 v[82:83], 0
	v_mov_b64_e32 v[84:85], 0
	v_mov_b64_e32 v[86:87], 0
	v_mov_b64_e32 v[88:89], 0
	v_mov_b64_e32 v[90:91], 0
	v_mov_b64_e32 v[92:93], 0
	v_mov_b64_e32 v[94:95], 0
	v_mov_b64_e32 v[96:97], 0
	v_mov_b64_e32 v[98:99], 0
	v_mov_b64_e32 v[100:101], 0
	v_mov_b64_e32 v[102:103], 0
	v_mov_b64_e32 v[104:105], 0
	v_mov_b64_e32 v[106:107], 0
	v_mov_b64_e32 v[108:109], 0
	v_mov_b64_e32 v[110:111], 0
	v_mov_b64_e32 v[112:113], 0
	v_mov_b64_e32 v[114:115], 0
	v_mov_b64_e32 v[116:117], 0
	v_mov_b64_e32 v[118:119], 0
	v_mov_b64_e32 v[120:121], 0
	v_mov_b64_e32 v[122:123], 0
	v_mov_b64_e32 v[124:125], 0
	v_mov_b64_e32 v[126:127], 0

;     __device__ __forceinline__ bool next(int i, Unit& u) const { const long L = (long)i * G + c; if (L >= map.total()) return false; map((int)L, u); return true; }
; template <class Epi, class Sched, bool SWAPD = false>
; __device__ __forceinline__ void gemm_phase(LAS unsigned char* lds, const Gemm g, const Sched& S, const Epi& E) {
;     ...
;         const bool has_next = S.next(ui + 1, nxt);
;         const char* nA = has_next ? (const char*)g.A + nxt.aoff : cA; const char* nB = has_next ? (const char*)g.Bt + nxt.boff : cB;
;         const int nt = cur.nt ? cur.nt : ntK;
;         for (int t = 0; t < nt; t += 2) {
;             const bool last = (t == nt - 2);
;             const char* a1 = cA + (size_t)(t + 1) * kstepA;
;             const char* a2 = last ? nA : cA + (size_t)(t + 2) * kstepA; const char* b2 = last ? nB : cB + (size_t)(t + 2) * kstep;
;             const char* a3 = a2 + kstepA; const char* b3 = b2 + kstep;
;     ...
; #pragma unroll
;         for (int a = 0; a < 2; ++a)
; #pragma unroll
;             for (int b = 0; b < 2; ++b)
; #pragma unroll
;                 for (int m = 0; m < 4; ++m)
; #pragma unroll
;                     for (int n = 0; n < 2; ++n) acc[a][b][m][n] = (f32x4){0.f, 0.f, 0.f, 0.f};
.LBB0_1120:
	s_add_u32 s26, s14, s22
	s_addc_u32 s27, s15, s23
	s_and_b64 s[28:29], s[6:7], exec
	s_cselect_b32 s58, s27, s35
	s_cselect_b32 s59, s26, s34
	s_add_u32 s28, s21, s24
	s_addc_u32 s29, s30, s25
	s_and_b64 s[38:39], s[6:7], exec
	s_cselect_b32 s60, s29, s37
	s_cselect_b32 s61, s28, s36
	s_add_u32 s62, s36, 0x100
	v_mov_b32_e32 v0, 0
	s_addc_u32 s63, s37, 0
	s_mov_b32 s64, -2
	v_mov_b64_e32 v[0:1], 0
	v_mov_b64_e32 v[2:3], 0
	v_mov_b64_e32 v[4:5], 0
	v_mov_b64_e32 v[6:7], 0
	v_mov_b64_e32 v[8:9], 0
	v_mov_b64_e32 v[10:11], 0
	v_mov_b64_e32 v[12:13], 0
	v_mov_b64_e32 v[14:15], 0
	v_mov_b64_e32 v[16:17], 0
	v_mov_b64_e32 v[18:19], 0
	v_mov_b64_e32 v[20:21], 0
	v_mov_b64_e32 v[22:23], 0
	v_mov_b64_e32 v[24:25], 0
	v_mov_b64_e32 v[26:27], 0
	v_mov_b64_e32 v[28:29], 0
	v_mov_b64_e32 v[30:31], 0
	v_mov_b64_e32 v[32:33], 0
	v_mov_b64_e32 v[34:35], 0
	v_mov_b64_e32 v[36:37], 0
	v_mov_b64_e32 v[38:39], 0
	v_mov_b64_e32 v[40:41], 0
	v_mov_b64_e32 v[42:43], 0
	v_mov_b64_e32 v[44:45], 0
	v_mov_b64_e32 v[46:47], 0
	v_mov_b64_e32 v[48:49], 0
	v_mov_b64_e32 v[50:51], 0
	v_mov_b64_e32 v[52:53], 0
	v_mov_b64_e32 v[54:55], 0
	v_mov_b64_e32 v[56:57], 0
	v_mov_b64_e32 v[58:59], 0
	v_mov_b64_e32 v[60:61], 0
	v_mov_b64_e32 v[62:63], 0
	v_mov_b64_e32 v[64:65], 0
	v_mov_b64_e32 v[66:67], 0
	v_mov_b64_e32 v[68:69], 0
	v_mov_b64_e32 v[70:71], 0
	v_mov_b64_e32 v[72:73], 0
	v_mov_b64_e32 v[74:75], 0
	v_mov_b64_e32 v[76:77], 0
	v_mov_b64_e32 v[78:79], 0
	v_mov_b64_e32 v[80:81], 0
	v_mov_b64_e32 v[82:83], 0
	v_mov_b64_e32 v[84:85], 0
	v_mov_b64_e32 v[86:87], 0
	v_mov_b64_e32 v[88:89], 0
	v_mov_b64_e32 v[90:91], 0
	v_mov_b64_e32 v[92:93], 0
	v_mov_b64_e32 v[94:95], 0
	v_mov_b64_e32 v[96:97], 0
	v_mov_b64_e32 v[98:99], 0
	v_mov_b64_e32 v[100:101], 0
	v_mov_b64_e32 v[102:103], 0
	v_mov_b64_e32 v[104:105], 0
	v_mov_b64_e32 v[106:107], 0
	v_mov_b64_e32 v[108:109], 0
	v_mov_b64_e32 v[110:111], 0
	v_mov_b64_e32 v[112:113], 0
	v_mov_b64_e32 v[114:115], 0
	v_mov_b64_e32 v[116:117], 0
	v_mov_b64_e32 v[118:119], 0
	v_mov_b64_e32 v[120:121], 0
	v_mov_b64_e32 v[122:123], 0
	v_mov_b64_e32 v[124:125], 0
	v_mov_b64_e32 v[126:127], 0

;     __device__ __forceinline__ bool next(int i, Unit& u) const { const long L = (long)i * G + c; if (L >= map.total()) return false; map((int)L, u); return true; }
; template <class Epi, class Sched, bool SWAPD = false>
; __device__ __forceinline__ void gemm_phase(LAS unsigned char* lds, const Gemm g, const Sched& S, const Epi& E) {
;     ...
;         const bool has_next = S.next(ui + 1, nxt);
;         const char* nA = has_next ? (const char*)g.A + nxt.aoff : cA; const char* nB = has_next ? (const char*)g.Bt + nxt.boff : cB;
;         const int nt = cur.nt ? cur.nt : ntK;
;         for (int t = 0; t < nt; t += 2) {
;             const bool last = (t == nt - 2);
;             const char* a1 = cA + (size_t)(t + 1) * kstepA;
;             const char* a2 = last ? nA : cA + (size_t)(t + 2) * kstepA; const char* b2 = last ? nB : cB + (size_t)(t + 2) * kstep;
;             const char* a3 = a2 + kstepA; const char* b3 = b2 + kstep;
;     ...
; #pragma unroll
;         for (int a = 0; a < 2; ++a)
; #pragma unroll
;             for (int b = 0; b < 2; ++b)
; #pragma unroll
;                 for (int m = 0; m < 4; ++m)
; #pragma unroll
;                     for (int n = 0; n < 2; ++n) acc[a][b][m][n] = (f32x4){0.f, 0.f, 0.f, 0.f};
.LBB0_1246:
	s_add_u32 s36, s18, s28
	s_addc_u32 s37, s19, s29
	s_and_b64 s[38:39], s[6:7], exec
	s_cselect_b32 s25, s37, s43
	s_cselect_b32 s27, s36, s42
	s_add_u32 s38, s21, s34
	s_addc_u32 s39, s23, s35
	s_and_b64 s[46:47], s[6:7], exec
	s_cselect_b32 s59, s39, s45
	s_cselect_b32 s60, s38, s44
	s_add_u32 s42, s42, 0x40080
	s_addc_u32 s43, s43, 0
	s_add_u32 s61, s44, 0x100
	v_mov_b32_e32 v0, 0
	s_addc_u32 s62, s45, 0
	s_mov_b32 s63, -2
	v_mov_b64_e32 v[0:1], 0
	v_mov_b64_e32 v[2:3], 0
	v_mov_b64_e32 v[4:5], 0
	v_mov_b64_e32 v[6:7], 0
	v_mov_b64_e32 v[8:9], 0
	v_mov_b64_e32 v[10:11], 0
	v_mov_b64_e32 v[12:13], 0
	v_mov_b64_e32 v[14:15], 0
	v_mov_b64_e32 v[16:17], 0
	v_mov_b64_e32 v[18:19], 0
	v_mov_b64_e32 v[20:21], 0
	v_mov_b64_e32 v[22:23], 0
	v_mov_b64_e32 v[24:25], 0
	v_mov_b64_e32 v[26:27], 0
	v_mov_b64_e32 v[28:29], 0
	v_mov_b64_e32 v[30:31], 0
	v_mov_b64_e32 v[32:33], 0
	v_mov_b64_e32 v[34:35], 0
	v_mov_b64_e32 v[36:37], 0
	v_mov_b64_e32 v[38:39], 0
	v_mov_b64_e32 v[40:41], 0
	v_mov_b64_e32 v[42:43], 0
	v_mov_b64_e32 v[44:45], 0
	v_mov_b64_e32 v[46:47], 0
	v_mov_b64_e32 v[48:49], 0
	v_mov_b64_e32 v[50:51], 0
	v_mov_b64_e32 v[52:53], 0
	v_mov_b64_e32 v[54:55], 0
	v_mov_b64_e32 v[56:57], 0
	v_mov_b64_e32 v[58:59], 0
	v_mov_b64_e32 v[60:61], 0
	v_mov_b64_e32 v[62:63], 0
	v_mov_b64_e32 v[64:65], 0
	v_mov_b64_e32 v[66:67], 0
	v_mov_b64_e32 v[68:69], 0
	v_mov_b64_e32 v[70:71], 0
	v_mov_b64_e32 v[72:73], 0
	v_mov_b64_e32 v[74:75], 0
	v_mov_b64_e32 v[76:77], 0
	v_mov_b64_e32 v[78:79], 0
	v_mov_b64_e32 v[80:81], 0
	v_mov_b64_e32 v[82:83], 0
	v_mov_b64_e32 v[84:85], 0
	v_mov_b64_e32 v[86:87], 0
	v_mov_b64_e32 v[88:89], 0
	v_mov_b64_e32 v[90:91], 0
	v_mov_b64_e32 v[92:93], 0
	v_mov_b64_e32 v[94:95], 0
	v_mov_b64_e32 v[96:97], 0
	v_mov_b64_e32 v[98:99], 0
	v_mov_b64_e32 v[100:101], 0
	v_mov_b64_e32 v[102:103], 0
	v_mov_b64_e32 v[104:105], 0
	v_mov_b64_e32 v[106:107], 0
	v_mov_b64_e32 v[108:109], 0
	v_mov_b64_e32 v[110:111], 0
	v_mov_b64_e32 v[112:113], 0
	v_mov_b64_e32 v[114:115], 0
	v_mov_b64_e32 v[116:117], 0
	v_mov_b64_e32 v[118:119], 0
	v_mov_b64_e32 v[120:121], 0
	v_mov_b64_e32 v[122:123], 0
	v_mov_b64_e32 v[124:125], 0
	v_mov_b64_e32 v[126:127], 0

;     __device__ __forceinline__ bool next(int i, Unit& u) const { const long L = (long)i * G + c; if (L >= map.total()) return false; map((int)L, u); return true; }
; template <class Epi, class Sched, bool SWAPD = false>
; __device__ __forceinline__ void gemm_phase(LAS unsigned char* lds, const Gemm g, const Sched& S, const Epi& E) {
;     ...
;         const bool has_next = S.next(ui + 1, nxt);
;         const char* nA = has_next ? (const char*)g.A + nxt.aoff : cA; const char* nB = has_next ? (const char*)g.Bt + nxt.boff : cB;
;         const int nt = cur.nt ? cur.nt : ntK;
;         for (int t = 0; t < nt; t += 2) {
;             const bool last = (t == nt - 2);
;             const char* a1 = cA + (size_t)(t + 1) * kstepA;
;             const char* a2 = last ? nA : cA + (size_t)(t + 2) * kstepA; const char* b2 = last ? nB : cB + (size_t)(t + 2) * kstep;
;             const char* a3 = a2 + kstepA; const char* b3 = b2 + kstep;
;     ...
; #pragma unroll
;         for (int a = 0; a < 2; ++a)
; #pragma unroll
;             for (int b = 0; b < 2; ++b)
; #pragma unroll
;                 for (int m = 0; m < 4; ++m)
; #pragma unroll
;                     for (int n = 0; n < 2; ++n) acc[a][b][m][n] = (f32x4){0.f, 0.f, 0.f, 0.f};
.LBB0_1530:
	s_add_u32 s36, s14, s28
	s_addc_u32 s37, s15, s29
	s_and_b64 s[38:39], s[6:7], exec
	s_cselect_b32 s9, s37, s41
	s_cselect_b32 s25, s36, s40
	s_add_u32 s38, s30, s34
	s_addc_u32 s39, s31, s35
	s_and_b64 s[44:45], s[6:7], exec
	s_cselect_b32 s27, s39, s43
	s_cselect_b32 s58, s38, s42
	s_add_u32 s40, s40, 0x20080
	s_addc_u32 s41, s41, 0
	s_add_u32 s59, s42, 0x100
	v_mov_b32_e32 v0, 0
	s_addc_u32 s60, s43, 0
	s_mov_b32 s61, -2
	v_mov_b64_e32 v[0:1], 0
	v_mov_b64_e32 v[2:3], 0
	v_mov_b64_e32 v[4:5], 0
	v_mov_b64_e32 v[6:7], 0
	v_mov_b64_e32 v[8:9], 0
	v_mov_b64_e32 v[10:11], 0
	v_mov_b64_e32 v[12:13], 0
	v_mov_b64_e32 v[14:15], 0
	v_mov_b64_e32 v[16:17], 0
	v_mov_b64_e32 v[18:19], 0
	v_mov_b64_e32 v[20:21], 0
	v_mov_b64_e32 v[22:23], 0
	v_mov_b64_e32 v[24:25], 0
	v_mov_b64_e32 v[26:27], 0
	v_mov_b64_e32 v[28:29], 0
	v_mov_b64_e32 v[30:31], 0
	v_mov_b64_e32 v[32:33], 0
	v_mov_b64_e32 v[34:35], 0
	v_mov_b64_e32 v[36:37], 0
	v_mov_b64_e32 v[38:39], 0
	v_mov_b64_e32 v[40:41], 0
	v_mov_b64_e32 v[42:43], 0
	v_mov_b64_e32 v[44:45], 0
	v_mov_b64_e32 v[46:47], 0
	v_mov_b64_e32 v[48:49], 0
	v_mov_b64_e32 v[50:51], 0
	v_mov_b64_e32 v[52:53], 0
	v_mov_b64_e32 v[54:55], 0
	v_mov_b64_e32 v[56:57], 0
	v_mov_b64_e32 v[58:59], 0
	v_mov_b64_e32 v[60:61], 0
	v_mov_b64_e32 v[62:63], 0
	v_mov_b64_e32 v[64:65], 0
	v_mov_b64_e32 v[66:67], 0
	v_mov_b64_e32 v[68:69], 0
	v_mov_b64_e32 v[70:71], 0
	v_mov_b64_e32 v[72:73], 0
	v_mov_b64_e32 v[74:75], 0
	v_mov_b64_e32 v[76:77], 0
	v_mov_b64_e32 v[78:79], 0
	v_mov_b64_e32 v[80:81], 0
	v_mov_b64_e32 v[82:83], 0
	v_mov_b64_e32 v[84:85], 0
	v_mov_b64_e32 v[86:87], 0
	v_mov_b64_e32 v[88:89], 0
	v_mov_b64_e32 v[90:91], 0
	v_mov_b64_e32 v[92:93], 0
	v_mov_b64_e32 v[94:95], 0
	v_mov_b64_e32 v[96:97], 0
	v_mov_b64_e32 v[98:99], 0
	v_mov_b64_e32 v[100:101], 0
	v_mov_b64_e32 v[102:103], 0
	v_mov_b64_e32 v[104:105], 0
	v_mov_b64_e32 v[106:107], 0
	v_mov_b64_e32 v[108:109], 0
	v_mov_b64_e32 v[110:111], 0
	v_mov_b64_e32 v[112:113], 0
	v_mov_b64_e32 v[114:115], 0
	v_mov_b64_e32 v[116:117], 0
	v_mov_b64_e32 v[118:119], 0
	v_mov_b64_e32 v[120:121], 0
	v_mov_b64_e32 v[122:123], 0
	v_mov_b64_e32 v[124:125], 0
	v_mov_b64_e32 v[126:127], 0

; template <class Epi, class Sched, bool SWAPD = false>
; __device__ __forceinline__ void gemm_phase(LAS unsigned char* lds, const Gemm g, const Sched& S, const Epi& E) {
;     ...
; #pragma unroll
;         for (int a = 0; a < 2; ++a)
; #pragma unroll
;             for (int b = 0; b < 2; ++b)
; #pragma unroll
;                 for (int m = 0; m < 4; ++m)
; #pragma unroll
;                     for (int n = 0; n < 2; ++n) acc[a][b][m][n] = (f32x4){0.f, 0.f, 0.f, 0.f};
;     __device__ __forceinline__ bool next(int i, Unit& u) const { const long L = (long)i * G + c; if (L >= map.total()) return false; map((int)L, u); return true; }
.LBB0_1660:
	s_add_i32 s55, s55, 1
	s_mul_i32 s6, s55, s3
	s_mul_hi_u32 s7, s55, s90
	s_add_i32 s7, s7, s6
	s_mul_i32 s6, s55, s90
	s_mov_b64 s[44:45], s[12:13]
	s_mov_b64 s[12:13], s[42:43]
	s_add_u32 s42, s6, s2
	s_mov_b32 s69, s8
	s_addc_u32 s43, s7, s70
	s_ashr_i32 s8, s42, 2
	s_mov_b32 s68, s29
	s_and_b32 s29, s42, 3
	s_ashr_i32 s9, s8, 31
	v_cmp_lt_i64_e64 s[6:7], s[42:43], v[142:143]
	s_lshl_b32 s46, s29, 10
	s_lshl_b64 s[42:43], s[8:9], 20
	s_or_b32 s42, s42, s46
	s_and_b64 s[46:47], s[6:7], exec
	s_cselect_b32 s12, s42, s12
	s_cselect_b32 s9, s43, s13
	s_add_u32 s12, s18, s12
	s_addc_u32 s13, s19, s9
	s_and_b64 s[46:47], s[6:7], exec
	s_cselect_b32 s9, s13, s45
	s_cselect_b32 s74, s12, s44
	s_add_u32 s75, s44, 0x100
	v_mov_b32_e32 v0, 0
	s_addc_u32 s76, s45, 0
	v_lshl_add_u64 v[144:145], s[44:45], 0, v[138:139]
	v_lshl_add_u64 v[146:147], s[44:45], 0, v[140:141]
	s_mov_b32 s77, -2
	s_mov_b64 s[44:45], 0
	v_mov_b64_e32 v[0:1], 0
	v_mov_b64_e32 v[2:3], 0
	v_mov_b64_e32 v[4:5], 0
	v_mov_b64_e32 v[6:7], 0
	v_mov_b64_e32 v[8:9], 0
	v_mov_b64_e32 v[10:11], 0
	v_mov_b64_e32 v[12:13], 0
	v_mov_b64_e32 v[14:15], 0
	v_mov_b64_e32 v[16:17], 0
	v_mov_b64_e32 v[18:19], 0
	v_mov_b64_e32 v[20:21], 0
	v_mov_b64_e32 v[22:23], 0
	v_mov_b64_e32 v[24:25], 0
	v_mov_b64_e32 v[26:27], 0
	v_mov_b64_e32 v[28:29], 0
	v_mov_b64_e32 v[30:31], 0
	v_mov_b64_e32 v[32:33], 0
	v_mov_b64_e32 v[34:35], 0
	v_mov_b64_e32 v[36:37], 0
	v_mov_b64_e32 v[38:39], 0
	v_mov_b64_e32 v[40:41], 0
	v_mov_b64_e32 v[42:43], 0
	v_mov_b64_e32 v[44:45], 0
	v_mov_b64_e32 v[46:47], 0
	v_mov_b64_e32 v[48:49], 0
	v_mov_b64_e32 v[50:51], 0
	v_mov_b64_e32 v[52:53], 0
	v_mov_b64_e32 v[54:55], 0
	v_mov_b64_e32 v[56:57], 0
	v_mov_b64_e32 v[58:59], 0
	v_mov_b64_e32 v[60:61], 0
	v_mov_b64_e32 v[62:63], 0
	v_mov_b64_e32 v[64:65], 0
	v_mov_b64_e32 v[66:67], 0
	v_mov_b64_e32 v[68:69], 0
	v_mov_b64_e32 v[70:71], 0
	v_mov_b64_e32 v[72:73], 0
	v_mov_b64_e32 v[74:75], 0
	v_mov_b64_e32 v[76:77], 0
	v_mov_b64_e32 v[78:79], 0
	v_mov_b64_e32 v[80:81], 0
	v_mov_b64_e32 v[82:83], 0
	v_mov_b64_e32 v[84:85], 0
	v_mov_b64_e32 v[86:87], 0
	v_mov_b64_e32 v[88:89], 0
	v_mov_b64_e32 v[90:91], 0
	v_mov_b64_e32 v[92:93], 0
	v_mov_b64_e32 v[94:95], 0
	v_mov_b64_e32 v[96:97], 0
	v_mov_b64_e32 v[98:99], 0
	v_mov_b64_e32 v[100:101], 0
	v_mov_b64_e32 v[102:103], 0
	v_mov_b64_e32 v[104:105], 0
	v_mov_b64_e32 v[106:107], 0
	v_mov_b64_e32 v[108:109], 0
	v_mov_b64_e32 v[110:111], 0
	v_mov_b64_e32 v[112:113], 0
	v_mov_b64_e32 v[114:115], 0
	v_mov_b64_e32 v[116:117], 0
	v_mov_b64_e32 v[118:119], 0
	v_mov_b64_e32 v[120:121], 0
	v_mov_b64_e32 v[122:123], 0
	v_mov_b64_e32 v[124:125], 0
	v_mov_b64_e32 v[126:127], 0

;     __device__ __forceinline__ bool next(int i, Unit& u) const { const long L = (long)i * G + c; if (L >= map.total()) return false; map((int)L, u); return true; }
; template <class Epi, class Sched, bool SWAPD = false>
; __device__ __forceinline__ void gemm_phase(LAS unsigned char* lds, const Gemm g, const Sched& S, const Epi& E) {
;     ...
;         const bool has_next = S.next(ui + 1, nxt);
;         const char* nA = has_next ? (const char*)g.A + nxt.aoff : cA; const char* nB = has_next ? (const char*)g.Bt + nxt.boff : cB;
;         const int nt = cur.nt ? cur.nt : ntK;
;         for (int t = 0; t < nt; t += 2) {
;             const bool last = (t == nt - 2);
;             const char* a1 = cA + (size_t)(t + 1) * kstepA;
;             const char* a2 = last ? nA : cA + (size_t)(t + 2) * kstepA; const char* b2 = last ? nB : cB + (size_t)(t + 2) * kstep;
;             const char* a3 = a2 + kstepA; const char* b3 = b2 + kstep;
;     ...
; #pragma unroll
;         for (int a = 0; a < 2; ++a)
; #pragma unroll
;             for (int b = 0; b < 2; ++b)
; #pragma unroll
;                 for (int m = 0; m < 4; ++m)
; #pragma unroll
;                     for (int n = 0; n < 2; ++n) acc[a][b][m][n] = (f32x4){0.f, 0.f, 0.f, 0.f};
;         cur = nxt; cA = nA; cB = nB; ++ui;
.LBB0_1736:
	s_add_u32 s34, s14, s26
	s_addc_u32 s35, s15, s27
	s_and_b64 s[36:37], s[6:7], exec
	s_cselect_b32 s23, s35, s41
	s_cselect_b32 s25, s34, s40
	s_add_u32 s36, s96, s28
	s_addc_u32 s37, s97, s29
	s_and_b64 s[44:45], s[6:7], exec
	s_cselect_b32 s56, s37, s43
	s_cselect_b32 s57, s36, s42
	s_add_u32 s40, s40, 0x40080
	s_addc_u32 s41, s41, 0
	s_add_u32 s58, s42, 0x100
	v_mov_b32_e32 v0, 0
	s_addc_u32 s59, s43, 0
	s_mov_b32 s60, -2
	v_mov_b64_e32 v[0:1], 0
	v_mov_b64_e32 v[2:3], 0
	v_mov_b64_e32 v[4:5], 0
	v_mov_b64_e32 v[6:7], 0
	v_mov_b64_e32 v[8:9], 0
	v_mov_b64_e32 v[10:11], 0
	v_mov_b64_e32 v[12:13], 0
	v_mov_b64_e32 v[14:15], 0
	v_mov_b64_e32 v[16:17], 0
	v_mov_b64_e32 v[18:19], 0
	v_mov_b64_e32 v[20:21], 0
	v_mov_b64_e32 v[22:23], 0
	v_mov_b64_e32 v[24:25], 0
	v_mov_b64_e32 v[26:27], 0
	v_mov_b64_e32 v[28:29], 0
	v_mov_b64_e32 v[30:31], 0
	v_mov_b64_e32 v[32:33], 0
	v_mov_b64_e32 v[34:35], 0
	v_mov_b64_e32 v[36:37], 0
	v_mov_b64_e32 v[38:39], 0
	v_mov_b64_e32 v[40:41], 0
	v_mov_b64_e32 v[42:43], 0
	v_mov_b64_e32 v[44:45], 0
	v_mov_b64_e32 v[46:47], 0
	v_mov_b64_e32 v[48:49], 0
	v_mov_b64_e32 v[50:51], 0
	v_mov_b64_e32 v[52:53], 0
	v_mov_b64_e32 v[54:55], 0
	v_mov_b64_e32 v[56:57], 0
	v_mov_b64_e32 v[58:59], 0
	v_mov_b64_e32 v[60:61], 0
	v_mov_b64_e32 v[62:63], 0
	v_mov_b64_e32 v[64:65], 0
	v_mov_b64_e32 v[66:67], 0
	v_mov_b64_e32 v[68:69], 0
	v_mov_b64_e32 v[70:71], 0
	v_mov_b64_e32 v[72:73], 0
	v_mov_b64_e32 v[74:75], 0
	v_mov_b64_e32 v[76:77], 0
	v_mov_b64_e32 v[78:79], 0
	v_mov_b64_e32 v[80:81], 0
	v_mov_b64_e32 v[82:83], 0
	v_mov_b64_e32 v[84:85], 0
	v_mov_b64_e32 v[86:87], 0
	v_mov_b64_e32 v[88:89], 0
	v_mov_b64_e32 v[90:91], 0
	v_mov_b64_e32 v[92:93], 0
	v_mov_b64_e32 v[94:95], 0
	v_mov_b64_e32 v[96:97], 0
	v_mov_b64_e32 v[98:99], 0
	v_mov_b64_e32 v[100:101], 0
	v_mov_b64_e32 v[102:103], 0
	v_mov_b64_e32 v[112:113], 0
	v_mov_b64_e32 v[114:115], 0
	v_mov_b64_e32 v[116:117], 0
	v_mov_b64_e32 v[118:119], 0
	v_mov_b64_e32 v[120:121], 0
	v_mov_b64_e32 v[122:123], 0
	v_mov_b64_e32 v[132:133], 0
	v_mov_b64_e32 v[134:135], 0
	v_mov_b64_e32 v[136:137], 0
	v_mov_b64_e32 v[138:139], 0
	v_mov_b64_e32 v[140:141], 0
	v_mov_b64_e32 v[142:143], 0

;     __device__ __forceinline__ bool next(int i, Unit& u) const { const long L = (long)i * G + c; if (L >= map.total()) return false; map((int)L, u); return true; }
; template <class Epi, class Sched, bool SWAPD = false>
; __device__ __forceinline__ void gemm_phase(LAS unsigned char* lds, const Gemm g, const Sched& S, const Epi& E) {
;     ...
;         const bool has_next = S.next(ui + 1, nxt);
;         const char* nA = has_next ? (const char*)g.A + nxt.aoff : cA; const char* nB = has_next ? (const char*)g.Bt + nxt.boff : cB;
;         const int nt = cur.nt ? cur.nt : ntK;
;         for (int t = 0; t < nt; t += 2) {
;             const bool last = (t == nt - 2);
;             const char* a1 = cA + (size_t)(t + 1) * kstepA;
;             const char* a2 = last ? nA : cA + (size_t)(t + 2) * kstepA; const char* b2 = last ? nB : cB + (size_t)(t + 2) * kstep;
;             const char* a3 = a2 + kstepA; const char* b3 = b2 + kstep;
;     ...
; #pragma unroll
;         for (int a = 0; a < 2; ++a)
; #pragma unroll
;             for (int b = 0; b < 2; ++b)
; #pragma unroll
;                 for (int m = 0; m < 4; ++m)
; #pragma unroll
;                     for (int n = 0; n < 2; ++n) acc[a][b][m][n] = (f32x4){0.f, 0.f, 0.f, 0.f};
;         cur = nxt; cA = nA; cB = nB; ++ui;
.LBB0_1862:
	s_add_u32 s28, s18, s24
	s_addc_u32 s29, s19, s25
	s_and_b64 s[30:31], s[6:7], exec
	s_cselect_b32 s21, s29, s37
	s_cselect_b32 s23, s28, s36
	s_add_u32 s30, s13, s26
	s_addc_u32 s31, s33, s27
	s_and_b64 s[40:41], s[6:7], exec
	s_cselect_b32 s54, s31, s39
	s_cselect_b32 s55, s30, s38
	s_add_u32 s36, s36, 0x40080
	s_addc_u32 s37, s37, 0
	s_add_u32 s56, s38, 0x100
	v_mov_b32_e32 v0, 0
	s_addc_u32 s57, s39, 0
	s_mov_b32 s58, -2
	v_mov_b64_e32 v[0:1], 0
	v_mov_b64_e32 v[2:3], 0
	v_mov_b64_e32 v[4:5], 0
	v_mov_b64_e32 v[6:7], 0
	v_mov_b64_e32 v[8:9], 0
	v_mov_b64_e32 v[10:11], 0
	v_mov_b64_e32 v[12:13], 0
	v_mov_b64_e32 v[14:15], 0
	v_mov_b64_e32 v[16:17], 0
	v_mov_b64_e32 v[18:19], 0
	v_mov_b64_e32 v[20:21], 0
	v_mov_b64_e32 v[22:23], 0
	v_mov_b64_e32 v[24:25], 0
	v_mov_b64_e32 v[26:27], 0
	v_mov_b64_e32 v[28:29], 0
	v_mov_b64_e32 v[30:31], 0
	v_mov_b64_e32 v[32:33], 0
	v_mov_b64_e32 v[34:35], 0
	v_mov_b64_e32 v[36:37], 0
	v_mov_b64_e32 v[38:39], 0
	v_mov_b64_e32 v[40:41], 0
	v_mov_b64_e32 v[42:43], 0
	v_mov_b64_e32 v[44:45], 0
	v_mov_b64_e32 v[46:47], 0
	v_mov_b64_e32 v[48:49], 0
	v_mov_b64_e32 v[50:51], 0
	v_mov_b64_e32 v[52:53], 0
	v_mov_b64_e32 v[54:55], 0
	v_mov_b64_e32 v[56:57], 0
	v_mov_b64_e32 v[58:59], 0
	v_mov_b64_e32 v[60:61], 0
	v_mov_b64_e32 v[62:63], 0
	v_mov_b64_e32 v[64:65], 0
	v_mov_b64_e32 v[66:67], 0
	v_mov_b64_e32 v[68:69], 0
	v_mov_b64_e32 v[70:71], 0
	v_mov_b64_e32 v[72:73], 0
	v_mov_b64_e32 v[74:75], 0
	v_mov_b64_e32 v[76:77], 0
	v_mov_b64_e32 v[78:79], 0
	v_mov_b64_e32 v[80:81], 0
	v_mov_b64_e32 v[82:83], 0
	v_mov_b64_e32 v[84:85], 0
	v_mov_b64_e32 v[86:87], 0
	v_mov_b64_e32 v[88:89], 0
	v_mov_b64_e32 v[90:91], 0
	v_mov_b64_e32 v[92:93], 0
	v_mov_b64_e32 v[94:95], 0
	v_mov_b64_e32 v[96:97], 0
	v_mov_b64_e32 v[98:99], 0
	v_mov_b64_e32 v[100:101], 0
	v_mov_b64_e32 v[102:103], 0
	v_mov_b64_e32 v[104:105], 0
	v_mov_b64_e32 v[106:107], 0
	v_mov_b64_e32 v[108:109], 0
	v_mov_b64_e32 v[110:111], 0
	v_mov_b64_e32 v[112:113], 0
	v_mov_b64_e32 v[114:115], 0
	v_mov_b64_e32 v[116:117], 0
	v_mov_b64_e32 v[118:119], 0
	v_mov_b64_e32 v[120:121], 0
	v_mov_b64_e32 v[122:123], 0
	v_mov_b64_e32 v[124:125], 0
	v_mov_b64_e32 v[126:127], 0

;     __device__ __forceinline__ bool next(int i, Unit& u) const { const long L = (long)i * G + c; if (L >= map.total()) return false; map((int)L, u); return true; }
; template <class Epi, class Sched, bool SWAPD = false>
; __device__ __forceinline__ void gemm_phase(LAS unsigned char* lds, const Gemm g, const Sched& S, const Epi& E) {
;     ...
;         const bool has_next = S.next(ui + 1, nxt);
;         const char* nA = has_next ? (const char*)g.A + nxt.aoff : cA; const char* nB = has_next ? (const char*)g.Bt + nxt.boff : cB;
;         const int nt = cur.nt ? cur.nt : ntK;
;         for (int t = 0; t < nt; t += 2) {
;             const bool last = (t == nt - 2);
;             const char* a1 = cA + (size_t)(t + 1) * kstepA;
;             const char* a2 = last ? nA : cA + (size_t)(t + 2) * kstepA; const char* b2 = last ? nB : cB + (size_t)(t + 2) * kstep;
;             const char* a3 = a2 + kstepA; const char* b3 = b2 + kstep;
;     ...
; #pragma unroll
;         for (int a = 0; a < 2; ++a)
; #pragma unroll
;             for (int b = 0; b < 2; ++b)
; #pragma unroll
;                 for (int m = 0; m < 4; ++m)
; #pragma unroll
;                     for (int n = 0; n < 2; ++n) acc[a][b][m][n] = (f32x4){0.f, 0.f, 0.f, 0.f};
;         cur = nxt; cA = nA; cB = nB; ++ui;
.LBB0_1939:
	s_add_u32 s16, s14, s10
	s_addc_u32 s17, s15, s11
	s_and_b64 s[18:19], s[0:1], exec
	s_cselect_b32 s47, s17, s21
	s_cselect_b32 s48, s16, s20
	s_add_u32 s18, s28, s12
	s_addc_u32 s19, s29, s13
	s_and_b64 s[24:25], s[0:1], exec
	s_cselect_b32 s49, s19, s23
	s_cselect_b32 s50, s18, s22
	s_add_u32 s51, s22, 0x100
	v_mov_b32_e32 v0, 0
	s_addc_u32 s52, s23, 0
	s_mov_b32 s53, -2
	v_mov_b64_e32 v[0:1], 0
	v_mov_b64_e32 v[2:3], 0
	v_mov_b64_e32 v[4:5], 0
	v_mov_b64_e32 v[6:7], 0
	v_mov_b64_e32 v[8:9], 0
	v_mov_b64_e32 v[10:11], 0
	v_mov_b64_e32 v[12:13], 0
	v_mov_b64_e32 v[14:15], 0
	v_mov_b64_e32 v[16:17], 0
	v_mov_b64_e32 v[18:19], 0
	v_mov_b64_e32 v[20:21], 0
	v_mov_b64_e32 v[22:23], 0
	v_mov_b64_e32 v[24:25], 0
	v_mov_b64_e32 v[26:27], 0
	v_mov_b64_e32 v[28:29], 0
	v_mov_b64_e32 v[30:31], 0
	v_mov_b64_e32 v[32:33], 0
	v_mov_b64_e32 v[34:35], 0
	v_mov_b64_e32 v[36:37], 0
	v_mov_b64_e32 v[38:39], 0
	v_mov_b64_e32 v[40:41], 0
	v_mov_b64_e32 v[42:43], 0
	v_mov_b64_e32 v[44:45], 0
	v_mov_b64_e32 v[46:47], 0
	v_mov_b64_e32 v[48:49], 0
	v_mov_b64_e32 v[50:51], 0
	v_mov_b64_e32 v[52:53], 0
	v_mov_b64_e32 v[54:55], 0
	v_mov_b64_e32 v[56:57], 0
	v_mov_b64_e32 v[58:59], 0
	v_mov_b64_e32 v[60:61], 0
	v_mov_b64_e32 v[62:63], 0
	v_mov_b64_e32 v[64:65], 0
	v_mov_b64_e32 v[66:67], 0
	v_mov_b64_e32 v[68:69], 0
	v_mov_b64_e32 v[70:71], 0
	v_mov_b64_e32 v[72:73], 0
	v_mov_b64_e32 v[74:75], 0
	v_mov_b64_e32 v[76:77], 0
	v_mov_b64_e32 v[78:79], 0
	v_mov_b64_e32 v[80:81], 0
	v_mov_b64_e32 v[82:83], 0
	v_mov_b64_e32 v[84:85], 0
	v_mov_b64_e32 v[86:87], 0
	v_mov_b64_e32 v[88:89], 0
	v_mov_b64_e32 v[90:91], 0
	v_mov_b64_e32 v[92:93], 0
	v_mov_b64_e32 v[94:95], 0
	v_mov_b64_e32 v[96:97], 0
	v_mov_b64_e32 v[98:99], 0
	v_mov_b64_e32 v[100:101], 0
	v_mov_b64_e32 v[102:103], 0
	v_mov_b64_e32 v[104:105], 0
	v_mov_b64_e32 v[106:107], 0
	v_mov_b64_e32 v[108:109], 0
	v_mov_b64_e32 v[110:111], 0
	v_mov_b64_e32 v[112:113], 0
	v_mov_b64_e32 v[114:115], 0
	v_mov_b64_e32 v[116:117], 0
	v_mov_b64_e32 v[118:119], 0
	v_mov_b64_e32 v[120:121], 0
	v_mov_b64_e32 v[122:123], 0
	v_mov_b64_e32 v[124:125], 0
	v_mov_b64_e32 v[126:127], 0
